# hn row loop: loop-invariant pointer kept in SGPRs instead of 4 s_load round trips per iteration; rows wait with counted vmcnt 9/7/5/3 when all four rows exist
# speedup vs baseline: 1.0073x; 1.0014x over previous
.LBB0_517:
	s_and_b64 vcc, exec, s[4:5]
	s_cbranch_vccz .LBB0_533
	v_mov_b32_e32 v0, v163
	v_readlane_b32 s0, v254, 0
	v_mov_b32_e32 v2, v163
	v_readlane_b32 s2, v254, 5
	v_ashrrev_i32_e32 v2, 6, v2
	v_lshl_add_u32 v66, s0, 3, v2
	v_cmp_gt_i32_e32 vcc, s33, v66
	s_and_saveexec_b64 s[4:5], vcc
	s_cbranch_execz .LBB0_703
	s_waitcnt lgkmcnt(0)
	v_readlane_b32 s10, v254, 25
	v_readlane_b32 s11, v254, 26
	s_load_dwordx2 s[6:7], s[10:11], 0xc8
	v_readlane_b32 s8, v254, 29
	v_readlane_b32 s9, v254, 30
	s_mov_b32 s12, s8
	s_ashr_i32 s13, s8, 31
	v_writelane_b32 v254, s8, 29
	s_lshl_b32 s0, s2, 3
	v_lshlrev_b32_e32 v0, 3, v0
	v_writelane_b32 v254, s9, 30
	s_lshl_b64 s[8:9], s[12:13], 11
	v_and_b32_e32 v58, 0x1f8, v0
	s_waitcnt lgkmcnt(0)
	s_add_u32 s6, s6, s8
	s_addc_u32 s7, s7, s9
	v_lshlrev_b32_e32 v0, 2, v58
	global_load_dwordx4 v[2:5], v0, s[6:7]
	global_load_dwordx4 v[6:9], v0, s[6:7] offset:16
	s_load_dwordx2 s[6:7], s[10:11], 0x118
	v_lshlrev_b32_e32 v0, 1, v58
	s_lshl_b32 s1, s2, 4
	s_mul_i32 s2, s2, 24
	s_waitcnt lgkmcnt(0)
	s_mov_b64 s[98:99], s[6:7]
	v_lshl_add_u64 v[10:11], s[6:7], 0, v[0:1]
	s_mov_b64 s[6:7], 0x934000
	v_lshl_add_u64 v[60:61], v[10:11], 0, s[6:7]
	v_mbcnt_hi_u32_b32 v10, -1, v203
	v_and_b32_e32 v12, 64, v10
	v_xor_b32_e32 v11, 1, v10
	v_add_u32_e32 v12, 64, v12
	v_cmp_lt_i32_e32 vcc, v11, v12
	v_readlane_b32 s6, v254, 33
	v_readlane_b32 s7, v254, 34
	v_cndmask_b32_e32 v11, v10, v11, vcc
	v_lshlrev_b32_e32 v59, 2, v11
	v_xor_b32_e32 v11, 2, v10
	v_cmp_lt_i32_e32 vcc, v11, v12
	v_lshl_add_u64 v[62:63], s[6:7], 0, v[0:1]
	s_mov_b64 s[6:7], 0
	v_cndmask_b32_e32 v11, v10, v11, vcc
	v_lshlrev_b32_e32 v72, 2, v11
	v_xor_b32_e32 v11, 4, v10
	v_cmp_lt_i32_e32 vcc, v11, v12
	s_nop 1
	v_cndmask_b32_e32 v11, v10, v11, vcc
	v_lshlrev_b32_e32 v73, 2, v11
	v_xor_b32_e32 v11, 8, v10
	v_cmp_lt_i32_e32 vcc, v11, v12
	s_nop 1
	v_cndmask_b32_e32 v10, v10, v11, vcc
	v_lshlrev_b32_e32 v74, 2, v10
	s_branch .LBB0_521

.LBB0_521:
	v_ashrrev_i32_e32 v67, 31, v66
	v_lshlrev_b64 v[46:47], 10, v[66:67]
	v_lshlrev_b64 v[54:55], 11, v[66:67]
	v_lshl_add_u64 v[70:71], v[62:63], 0, v[54:55]
	v_lshl_add_u64 v[46:47], v[60:61], 0, v[46:47]
	global_load_dwordx4 v[50:53], v[70:71], off offset:512
	s_nop 0
	global_load_dwordx4 v[46:49], v[46:47], off
	v_lshlrev_b32_e32 v0, 1, v58
	v_add_u32_e32 v64, s0, v66
	v_ashrrev_i32_e32 v65, 31, v64
	v_lshl_add_u64 v[54:55], s[98:99], 0, v[54:55]
	v_lshl_add_u64 v[54:55], v[54:55], 0, v[0:1]
	v_add_co_u32_e32 v54, vcc, 0x8134000, v54
	s_nop 1
	v_addc_co_u32_e32 v55, vcc, 0, v55, vcc
	global_load_dwordx4 v[54:57], v[54:55], off offset:1024
	v_cmp_gt_i32_e32 vcc, s33, v64
	s_and_saveexec_b64 s[8:9], vcc
	s_cbranch_execz .LBB0_523
	v_lshlrev_b64 v[18:19], 10, v[64:65]
	v_lshlrev_b64 v[34:35], 11, v[64:65]
	v_lshl_add_u64 v[20:21], v[62:63], 0, v[34:35]
	v_lshl_add_u64 v[30:31], v[60:61], 0, v[18:19]
	global_load_dwordx4 v[18:21], v[20:21], off offset:512
	s_nop 0
	global_load_dwordx4 v[30:33], v[30:31], off
	v_lshl_add_u64 v[34:35], s[98:99], 0, v[34:35]
	v_lshl_add_u64 v[34:35], v[34:35], 0, v[0:1]
	v_add_co_u32_e32 v34, vcc, 0x8134000, v34
	s_nop 1
	v_addc_co_u32_e32 v35, vcc, 0, v35, vcc
	global_load_dwordx4 v[34:37], v[34:35], off offset:1024
.LBB0_523:
	s_or_b64 exec, exec, s[8:9]
	v_add_u32_e32 v68, s1, v66
	v_cmp_gt_i32_e32 vcc, s33, v68
	v_ashrrev_i32_e32 v69, 31, v68
	s_and_saveexec_b64 s[8:9], vcc
	s_cbranch_execz .LBB0_525
	v_lshlrev_b64 v[14:15], 10, v[68:69]
	v_lshlrev_b64 v[42:43], 11, v[68:69]
	v_lshl_add_u64 v[16:17], v[62:63], 0, v[42:43]
	v_lshl_add_u64 v[26:27], v[60:61], 0, v[14:15]
	global_load_dwordx4 v[14:17], v[16:17], off offset:512
	s_nop 0
	global_load_dwordx4 v[26:29], v[26:27], off
	v_lshl_add_u64 v[42:43], s[98:99], 0, v[42:43]
	v_lshl_add_u64 v[42:43], v[42:43], 0, v[0:1]
	v_add_co_u32_e32 v42, vcc, 0x8134000, v42
	s_nop 1
	v_addc_co_u32_e32 v43, vcc, 0, v43, vcc
	global_load_dwordx4 v[42:45], v[42:43], off offset:1024
.LBB0_525:
	s_or_b64 exec, exec, s[8:9]
	v_add_u32_e32 v66, s2, v66
	v_cmp_gt_i32_e32 vcc, s33, v66
	v_ashrrev_i32_e32 v67, 31, v66
	s_and_saveexec_b64 s[8:9], vcc
	s_cbranch_execz .LBB0_527
	v_lshlrev_b64 v[10:11], 10, v[66:67]
	v_lshlrev_b64 v[38:39], 11, v[66:67]
	v_lshl_add_u64 v[12:13], v[62:63], 0, v[38:39]
	v_lshl_add_u64 v[22:23], v[60:61], 0, v[10:11]
	global_load_dwordx4 v[10:13], v[12:13], off offset:512
	s_nop 0
	global_load_dwordx4 v[22:25], v[22:23], off
	v_lshl_add_u64 v[38:39], s[98:99], 0, v[38:39]
	v_lshl_add_u64 v[38:39], v[38:39], 0, v[0:1]
	v_add_co_u32_e32 v38, vcc, 0x8134000, v38
	s_nop 1
	v_addc_co_u32_e32 v39, vcc, 0, v39, vcc
	global_load_dwordx4 v[38:41], v[38:39], off offset:1024
.LBB0_527:
	s_or_b64 exec, exec, s[8:9]
	v_readfirstlane_b32 s3, v66
	s_cmp_lt_i32 s3, s33
	s_cbranch_scc1 .Lhn_all_rows
	s_waitcnt vmcnt(0)
.Lhn_all_rows:
	s_waitcnt vmcnt(9)
	v_lshlrev_b32_e32 v0, 16, v54
	v_and_b32_e32 v54, 0xffff0000, v54
	v_mul_f32_e32 v0, 0xbfb8aa3b, v0
	v_lshlrev_b32_e32 v75, 16, v55
	v_exp_f32_e32 v0, v0
	v_mul_f32_e32 v54, 0xbfb8aa3b, v54
	v_and_b32_e32 v76, 0xffff0000, v55
	v_exp_f32_e32 v55, v54
	v_mul_f32_e32 v54, 0xbfb8aa3b, v75
	v_lshlrev_b32_e32 v84, 16, v56
	v_and_b32_e32 v85, 0xffff0000, v56
	v_exp_f32_e32 v56, v54
	v_add_f32_e32 v0, 1.0, v0
	v_rcp_f32_e32 v54, v0
	v_add_f32_e32 v0, 1.0, v55
	v_rcp_f32_e32 v55, v0
	v_add_f32_e32 v0, 1.0, v56
	v_mul_f32_e32 v56, 0xbfb8aa3b, v76
	v_lshlrev_b32_e32 v86, 16, v57
	v_and_b32_e32 v87, 0xffff0000, v57
	v_exp_f32_e32 v75, v56
	v_lshlrev_b32_e32 v56, 16, v53
	v_and_b32_e32 v57, 0xffff0000, v53
	v_lshlrev_b32_e32 v78, 16, v52
	v_and_b32_e32 v79, 0xffff0000, v52
	v_lshlrev_b32_e32 v52, 16, v48
	v_and_b32_e32 v53, 0xffff0000, v48
	v_lshlrev_b32_e32 v76, 16, v49
	v_and_b32_e32 v77, 0xffff0000, v49
	v_pk_add_f32 v[48:49], v[78:79], v[52:53]
	v_lshlrev_b32_e32 v78, 16, v51
	v_and_b32_e32 v79, 0xffff0000, v51
	v_lshlrev_b32_e32 v82, 16, v50
	v_and_b32_e32 v83, 0xffff0000, v50
	v_lshlrev_b32_e32 v50, 16, v46
	v_and_b32_e32 v51, 0xffff0000, v46
	v_lshlrev_b32_e32 v80, 16, v47
	v_and_b32_e32 v81, 0xffff0000, v47
	v_pk_add_f32 v[46:47], v[82:83], v[50:51]
	v_pk_add_f32 v[78:79], v[78:79], v[80:81]
	v_pk_mul_f32 v[50:51], v[46:47], v[46:47]
	v_pk_mul_f32 v[80:81], v[78:79], v[78:79]
	v_add_f32_e32 v50, v50, v51
	v_add_f32_e32 v50, v80, v50
	v_pk_mul_f32 v[52:53], v[48:49], v[48:49]
	v_add_f32_e32 v50, v81, v50
	v_pk_add_f32 v[56:57], v[56:57], v[76:77]
	v_add_f32_e32 v50, v52, v50
	v_pk_mul_f32 v[76:77], v[56:57], v[56:57]
	v_add_f32_e32 v50, v53, v50
	v_add_f32_e32 v50, v76, v50
	v_add_f32_e32 v51, v77, v50
	ds_bpermute_b32 v52, v59, v51
	v_rcp_f32_e32 v50, v0
	v_add_f32_e32 v0, 1.0, v75
	v_mul_f32_e32 v53, 0xbfb8aa3b, v84
	v_exp_f32_e32 v53, v53
	s_waitcnt lgkmcnt(0)
	v_add_f32_e32 v52, v51, v52
	ds_bpermute_b32 v75, v72, v52
	v_rcp_f32_e32 v51, v0
	v_add_f32_e32 v0, 1.0, v53
	v_mul_f32_e32 v53, 0xbfb8aa3b, v85
	v_exp_f32_e32 v53, v53
	s_waitcnt lgkmcnt(0)
	v_add_f32_e32 v75, v52, v75
	ds_bpermute_b32 v76, v73, v75
	v_rcp_f32_e32 v52, v0
	v_add_f32_e32 v0, 1.0, v53
	v_mul_f32_e32 v53, 0xbfb8aa3b, v86
	v_exp_f32_e32 v77, v53
	s_waitcnt lgkmcnt(0)
	v_add_f32_e32 v75, v75, v76
	ds_bpermute_b32 v76, v74, v75
	s_mov_b32 s3, 0x800000
	v_rcp_f32_e32 v53, v0
	v_add_f32_e32 v0, 1.0, v77
	v_mul_f32_e32 v77, 0xbfb8aa3b, v87
	s_waitcnt lgkmcnt(0)
	v_add_f32_e32 v75, v75, v76
	v_fmamk_f32 v75, v75, 0x3c000000, v162
	v_mul_f32_e32 v76, 0x4b800000, v75
	v_cmp_gt_f32_e32 vcc, s3, v75
	v_exp_f32_e32 v77, v77
	s_nop 0
	v_cndmask_b32_e32 v75, v75, v76, vcc
	v_rsq_f32_e32 v75, v75
	v_rcp_f32_e32 v76, v0
	v_add_f32_e32 v0, 1.0, v77
	v_rcp_f32_e32 v77, v0
	v_mul_f32_e32 v0, 0x45800000, v75
	v_cndmask_b32_e32 v0, v75, v0, vcc
	v_pk_mul_f32 v[46:47], v[46:47], v[0:1] op_sel_hi:[1,0]
	v_pk_mul_f32 v[48:49], v[48:49], v[0:1] op_sel_hi:[1,0]
	v_pk_mul_f32 v[46:47], v[2:3], v[46:47]
	v_pk_mul_f32 v[48:49], v[6:7], v[48:49]
	v_pk_mul_f32 v[46:47], v[54:55], v[46:47]
	v_pk_mul_f32 v[54:55], v[78:79], v[0:1] op_sel_hi:[1,0]
	v_pk_mul_f32 v[48:49], v[52:53], v[48:49]
	v_pk_mul_f32 v[52:53], v[56:57], v[0:1] op_sel_hi:[1,0]
	v_pk_mul_f32 v[54:55], v[4:5], v[54:55]
	v_pk_mul_f32 v[52:53], v[8:9], v[52:53]
	v_pk_mul_f32 v[50:51], v[50:51], v[54:55]
	v_pk_mul_f32 v[52:53], v[76:77], v[52:53]
	v_cvt_pk_bf16_f32 v46, v46, v47
	v_cvt_pk_bf16_f32 v47, v50, v51
	v_cvt_pk_bf16_f32 v48, v48, v49
	v_cvt_pk_bf16_f32 v49, v52, v53
	v_cmp_gt_i32_e32 vcc, s33, v64
	global_store_dwordx4 v[70:71], v[46:49], off offset:512
	s_and_saveexec_b64 s[8:9], vcc
	s_cbranch_execnz .LBB0_530
	s_or_b64 exec, exec, s[8:9]
	v_cmp_gt_i32_e32 vcc, s33, v68
	s_and_saveexec_b64 s[8:9], vcc
	s_cbranch_execnz .LBB0_531

.LBB0_530:
	s_waitcnt vmcnt(7)
	v_lshlrev_b32_e32 v0, 16, v34
	v_and_b32_e32 v46, 0xffff0000, v34
	v_mul_f32_e32 v0, 0xbfb8aa3b, v0
	v_lshlrev_b32_e32 v47, 16, v35
	v_exp_f32_e32 v0, v0
	v_mul_f32_e32 v46, 0xbfb8aa3b, v46
	v_exp_f32_e32 v49, v46
	v_mul_f32_e32 v46, 0xbfb8aa3b, v47
	v_lshlrev_b32_e32 v76, 16, v18
	v_and_b32_e32 v77, 0xffff0000, v18
	v_lshlrev_b32_e32 v78, 16, v30
	v_and_b32_e32 v79, 0xffff0000, v30
	v_exp_f32_e32 v50, v46
	v_lshlrev_b32_e32 v56, 16, v19
	v_and_b32_e32 v57, 0xffff0000, v19
	v_lshlrev_b32_e32 v70, 16, v31
	v_and_b32_e32 v71, 0xffff0000, v31
	v_pk_add_f32 v[76:77], v[76:77], v[78:79]
	v_pk_add_f32 v[56:57], v[56:57], v[70:71]
	v_pk_mul_f32 v[78:79], v[76:77], v[76:77]
	v_and_b32_e32 v48, 0xffff0000, v35
	v_add_f32_e32 v0, 1.0, v0
	v_lshlrev_b32_e32 v52, 16, v20
	v_and_b32_e32 v53, 0xffff0000, v20
	v_lshlrev_b32_e32 v54, 16, v32
	v_and_b32_e32 v55, 0xffff0000, v32
	v_pk_mul_f32 v[70:71], v[56:57], v[56:57]
	v_add_f32_e32 v78, v78, v79
	v_rcp_f32_e32 v46, v0
	v_add_f32_e32 v0, 1.0, v49
	v_mul_f32_e32 v48, 0xbfb8aa3b, v48
	v_pk_add_f32 v[52:53], v[52:53], v[54:55]
	v_add_f32_e32 v70, v70, v78
	v_rcp_f32_e32 v47, v0
	v_add_f32_e32 v0, 1.0, v50
	v_exp_f32_e32 v83, v48
	v_lshlrev_b32_e32 v48, 16, v21
	v_and_b32_e32 v49, 0xffff0000, v21
	v_lshlrev_b32_e32 v50, 16, v33
	v_and_b32_e32 v51, 0xffff0000, v33
	v_pk_mul_f32 v[54:55], v[52:53], v[52:53]
	v_add_f32_e32 v70, v71, v70
	v_pk_add_f32 v[48:49], v[48:49], v[50:51]
	v_add_f32_e32 v54, v54, v70
	v_pk_mul_f32 v[50:51], v[48:49], v[48:49]
	v_add_f32_e32 v54, v55, v54
	v_add_f32_e32 v50, v50, v54
	v_add_f32_e32 v51, v51, v50
	ds_bpermute_b32 v54, v59, v51
	v_lshlrev_b32_e32 v75, 16, v36
	v_mul_f32_e32 v55, 0xbfb8aa3b, v75
	v_exp_f32_e32 v55, v55
	v_and_b32_e32 v80, 0xffff0000, v36
	s_waitcnt lgkmcnt(0)
	v_add_f32_e32 v54, v51, v54
	ds_bpermute_b32 v70, v72, v54
	v_rcp_f32_e32 v50, v0
	v_add_f32_e32 v0, 1.0, v83
	v_rcp_f32_e32 v51, v0
	v_add_f32_e32 v0, 1.0, v55
	s_waitcnt lgkmcnt(0)
	v_add_f32_e32 v70, v54, v70
	ds_bpermute_b32 v71, v73, v70
	v_mul_f32_e32 v55, 0xbfb8aa3b, v80
	v_exp_f32_e32 v55, v55
	v_lshlrev_b32_e32 v81, 16, v37
	v_rcp_f32_e32 v54, v0
	s_waitcnt lgkmcnt(0)
	v_add_f32_e32 v70, v70, v71
	ds_bpermute_b32 v71, v74, v70
	v_add_f32_e32 v0, 1.0, v55
	v_mul_f32_e32 v55, 0xbfb8aa3b, v81
	v_exp_f32_e32 v75, v55
	v_and_b32_e32 v82, 0xffff0000, v37
	s_waitcnt lgkmcnt(0)
	v_add_f32_e32 v70, v70, v71
	v_fmamk_f32 v70, v70, 0x3c000000, v162
	v_rcp_f32_e32 v55, v0
	v_add_f32_e32 v0, 1.0, v75
	v_mul_f32_e32 v75, 0xbfb8aa3b, v82
	v_mul_f32_e32 v71, 0x4b800000, v70
	v_cmp_gt_f32_e32 vcc, s3, v70
	v_exp_f32_e32 v75, v75
	s_nop 0
	v_cndmask_b32_e32 v70, v70, v71, vcc
	v_rsq_f32_e32 v78, v70
	v_rcp_f32_e32 v70, v0
	v_add_f32_e32 v0, 1.0, v75
	v_rcp_f32_e32 v71, v0
	v_mul_f32_e32 v0, 0x45800000, v78
	v_cndmask_b32_e32 v0, v78, v0, vcc
	v_pk_mul_f32 v[76:77], v[76:77], v[0:1] op_sel_hi:[1,0]
	v_pk_mul_f32 v[56:57], v[56:57], v[0:1] op_sel_hi:[1,0]
	v_pk_mul_f32 v[76:77], v[2:3], v[76:77]
	v_pk_mul_f32 v[56:57], v[4:5], v[56:57]
	v_pk_mul_f32 v[52:53], v[52:53], v[0:1] op_sel_hi:[1,0]
	v_pk_mul_f32 v[48:49], v[48:49], v[0:1] op_sel_hi:[1,0]
	v_pk_mul_f32 v[46:47], v[46:47], v[76:77]
	v_pk_mul_f32 v[50:51], v[50:51], v[56:57]
	v_pk_mul_f32 v[52:53], v[6:7], v[52:53]
	v_pk_mul_f32 v[48:49], v[8:9], v[48:49]
	v_pk_mul_f32 v[52:53], v[54:55], v[52:53]
	v_pk_mul_f32 v[54:55], v[70:71], v[48:49]
	v_cvt_pk_bf16_f32 v46, v46, v47
	v_cvt_pk_bf16_f32 v47, v50, v51
	v_lshlrev_b64 v[50:51], 11, v[64:65]
	v_cvt_pk_bf16_f32 v48, v52, v53
	v_cvt_pk_bf16_f32 v49, v54, v55
	v_lshl_add_u64 v[50:51], v[62:63], 0, v[50:51]
	global_store_dwordx4 v[50:51], v[46:49], off offset:512
	s_or_b64 exec, exec, s[8:9]
	v_cmp_gt_i32_e32 vcc, s33, v68
	s_and_saveexec_b64 s[8:9], vcc
	s_cbranch_execz .LBB0_529
.LBB0_531:
	s_waitcnt vmcnt(5)
	v_lshlrev_b32_e32 v0, 16, v42
	v_and_b32_e32 v46, 0xffff0000, v42
	v_mul_f32_e32 v0, 0xbfb8aa3b, v0
	v_lshlrev_b32_e32 v47, 16, v43
	v_exp_f32_e32 v0, v0
	v_mul_f32_e32 v46, 0xbfb8aa3b, v46
	v_exp_f32_e32 v49, v46
	v_mul_f32_e32 v46, 0xbfb8aa3b, v47
	v_lshlrev_b32_e32 v76, 16, v14
	v_and_b32_e32 v77, 0xffff0000, v14
	v_lshlrev_b32_e32 v78, 16, v26
	v_and_b32_e32 v79, 0xffff0000, v26
	v_exp_f32_e32 v50, v46
	v_lshlrev_b32_e32 v56, 16, v15
	v_and_b32_e32 v57, 0xffff0000, v15
	v_lshlrev_b32_e32 v70, 16, v27
	v_and_b32_e32 v71, 0xffff0000, v27
	v_pk_add_f32 v[76:77], v[76:77], v[78:79]
	v_pk_add_f32 v[56:57], v[56:57], v[70:71]
	v_pk_mul_f32 v[78:79], v[76:77], v[76:77]
	v_and_b32_e32 v48, 0xffff0000, v43
	v_add_f32_e32 v0, 1.0, v0
	v_lshlrev_b32_e32 v52, 16, v16
	v_and_b32_e32 v53, 0xffff0000, v16
	v_lshlrev_b32_e32 v54, 16, v28
	v_and_b32_e32 v55, 0xffff0000, v28
	v_pk_mul_f32 v[70:71], v[56:57], v[56:57]
	v_add_f32_e32 v78, v78, v79
	v_rcp_f32_e32 v46, v0
	v_add_f32_e32 v0, 1.0, v49
	v_mul_f32_e32 v48, 0xbfb8aa3b, v48
	v_pk_add_f32 v[52:53], v[52:53], v[54:55]
	v_add_f32_e32 v70, v70, v78
	v_rcp_f32_e32 v47, v0
	v_add_f32_e32 v0, 1.0, v50
	v_exp_f32_e32 v82, v48
	v_lshlrev_b32_e32 v48, 16, v17
	v_and_b32_e32 v49, 0xffff0000, v17
	v_lshlrev_b32_e32 v50, 16, v29
	v_and_b32_e32 v51, 0xffff0000, v29
	v_pk_mul_f32 v[54:55], v[52:53], v[52:53]
	v_add_f32_e32 v70, v71, v70
	v_pk_add_f32 v[48:49], v[48:49], v[50:51]
	v_add_f32_e32 v54, v54, v70
	v_pk_mul_f32 v[50:51], v[48:49], v[48:49]
	v_add_f32_e32 v54, v55, v54
	v_add_f32_e32 v50, v50, v54
	v_add_f32_e32 v51, v51, v50
	ds_bpermute_b32 v54, v59, v51
	v_lshlrev_b32_e32 v65, 16, v44
	v_mul_f32_e32 v55, 0xbfb8aa3b, v65
	v_exp_f32_e32 v55, v55
	v_and_b32_e32 v75, 0xffff0000, v44
	s_waitcnt lgkmcnt(0)
	v_add_f32_e32 v54, v51, v54
	ds_bpermute_b32 v65, v72, v54
	v_rcp_f32_e32 v50, v0
	v_add_f32_e32 v0, 1.0, v82
	v_rcp_f32_e32 v51, v0
	v_add_f32_e32 v0, 1.0, v55
	s_waitcnt lgkmcnt(0)
	v_add_f32_e32 v65, v54, v65
	ds_bpermute_b32 v70, v73, v65
	v_mul_f32_e32 v55, 0xbfb8aa3b, v75
	v_exp_f32_e32 v55, v55
	v_lshlrev_b32_e32 v80, 16, v45
	v_rcp_f32_e32 v54, v0
	s_waitcnt lgkmcnt(0)
	v_add_f32_e32 v65, v65, v70
	ds_bpermute_b32 v70, v74, v65
	v_add_f32_e32 v0, 1.0, v55
	v_mul_f32_e32 v55, 0xbfb8aa3b, v80
	v_exp_f32_e32 v71, v55
	v_and_b32_e32 v81, 0xffff0000, v45
	s_waitcnt lgkmcnt(0)
	v_add_f32_e32 v65, v65, v70
	v_fmamk_f32 v65, v65, 0x3c000000, v162
	v_rcp_f32_e32 v55, v0
	v_add_f32_e32 v0, 1.0, v71
	v_mul_f32_e32 v71, 0xbfb8aa3b, v81
	v_mul_f32_e32 v70, 0x4b800000, v65
	v_cmp_gt_f32_e32 vcc, s3, v65
	v_exp_f32_e32 v71, v71
	s_nop 0
	v_cndmask_b32_e32 v65, v65, v70, vcc
	v_rsq_f32_e32 v65, v65
	v_rcp_f32_e32 v70, v0
	v_add_f32_e32 v0, 1.0, v71
	v_rcp_f32_e32 v71, v0
	v_mul_f32_e32 v0, 0x45800000, v65
	v_cndmask_b32_e32 v0, v65, v0, vcc
	v_pk_mul_f32 v[76:77], v[76:77], v[0:1] op_sel_hi:[1,0]
	v_pk_mul_f32 v[56:57], v[56:57], v[0:1] op_sel_hi:[1,0]
	v_pk_mul_f32 v[76:77], v[2:3], v[76:77]
	v_pk_mul_f32 v[56:57], v[4:5], v[56:57]
	v_pk_mul_f32 v[52:53], v[52:53], v[0:1] op_sel_hi:[1,0]
	v_pk_mul_f32 v[48:49], v[48:49], v[0:1] op_sel_hi:[1,0]
	v_pk_mul_f32 v[46:47], v[46:47], v[76:77]
	v_pk_mul_f32 v[50:51], v[50:51], v[56:57]
	v_pk_mul_f32 v[52:53], v[6:7], v[52:53]
	v_pk_mul_f32 v[48:49], v[8:9], v[48:49]
	v_pk_mul_f32 v[52:53], v[54:55], v[52:53]
	v_pk_mul_f32 v[54:55], v[70:71], v[48:49]
	v_cvt_pk_bf16_f32 v46, v46, v47
	v_cvt_pk_bf16_f32 v47, v50, v51
	v_lshlrev_b64 v[50:51], 11, v[68:69]
	v_cvt_pk_bf16_f32 v48, v52, v53
	v_cvt_pk_bf16_f32 v49, v54, v55
	v_lshl_add_u64 v[50:51], v[62:63], 0, v[50:51]
	global_store_dwordx4 v[50:51], v[46:49], off offset:512
	s_or_b64 exec, exec, s[8:9]
	v_cmp_gt_i32_e32 vcc, s33, v66
	s_and_saveexec_b64 s[8:9], vcc
	s_cbranch_execz .LBB0_520
.LBB0_532:
	s_waitcnt vmcnt(3)
	v_lshlrev_b32_e32 v0, 16, v38
	v_and_b32_e32 v46, 0xffff0000, v38
	v_mul_f32_e32 v0, 0xbfb8aa3b, v0
	v_lshlrev_b32_e32 v47, 16, v39
	v_exp_f32_e32 v0, v0
	v_mul_f32_e32 v46, 0xbfb8aa3b, v46
	v_exp_f32_e32 v49, v46
	v_mul_f32_e32 v46, 0xbfb8aa3b, v47
	v_lshlrev_b32_e32 v70, 16, v10
	v_and_b32_e32 v71, 0xffff0000, v10
	v_lshlrev_b32_e32 v76, 16, v22
	v_and_b32_e32 v77, 0xffff0000, v22
	v_exp_f32_e32 v50, v46
	v_lshlrev_b32_e32 v56, 16, v11
	v_and_b32_e32 v57, 0xffff0000, v11
	v_lshlrev_b32_e32 v68, 16, v23
	v_and_b32_e32 v69, 0xffff0000, v23
	v_pk_add_f32 v[70:71], v[70:71], v[76:77]
	v_pk_add_f32 v[56:57], v[56:57], v[68:69]
	v_pk_mul_f32 v[76:77], v[70:71], v[70:71]
	v_and_b32_e32 v48, 0xffff0000, v39
	v_add_f32_e32 v0, 1.0, v0
	v_lshlrev_b32_e32 v52, 16, v12
	v_and_b32_e32 v53, 0xffff0000, v12
	v_lshlrev_b32_e32 v54, 16, v24
	v_and_b32_e32 v55, 0xffff0000, v24
	v_pk_mul_f32 v[68:69], v[56:57], v[56:57]
	v_add_f32_e32 v76, v76, v77
	v_rcp_f32_e32 v46, v0
	v_add_f32_e32 v0, 1.0, v49
	v_mul_f32_e32 v48, 0xbfb8aa3b, v48
	v_pk_add_f32 v[52:53], v[52:53], v[54:55]
	v_add_f32_e32 v68, v68, v76
	v_rcp_f32_e32 v47, v0
	v_add_f32_e32 v0, 1.0, v50
	v_exp_f32_e32 v80, v48
	v_lshlrev_b32_e32 v48, 16, v13
	v_and_b32_e32 v49, 0xffff0000, v13
	v_lshlrev_b32_e32 v50, 16, v25
	v_and_b32_e32 v51, 0xffff0000, v25
	v_pk_mul_f32 v[54:55], v[52:53], v[52:53]
	v_add_f32_e32 v68, v69, v68
	v_pk_add_f32 v[48:49], v[48:49], v[50:51]
	v_add_f32_e32 v54, v54, v68
	v_pk_mul_f32 v[50:51], v[48:49], v[48:49]
	v_add_f32_e32 v54, v55, v54
	v_add_f32_e32 v50, v50, v54
	v_add_f32_e32 v51, v51, v50
	ds_bpermute_b32 v54, v59, v51
	v_lshlrev_b32_e32 v65, 16, v40
	v_mul_f32_e32 v55, 0xbfb8aa3b, v65
	v_exp_f32_e32 v55, v55
	v_and_b32_e32 v75, 0xffff0000, v40
	s_waitcnt lgkmcnt(0)
	v_add_f32_e32 v54, v51, v54
	ds_bpermute_b32 v65, v72, v54
	v_rcp_f32_e32 v50, v0
	v_add_f32_e32 v0, 1.0, v80
	v_rcp_f32_e32 v51, v0
	v_add_f32_e32 v0, 1.0, v55
	s_waitcnt lgkmcnt(0)
	v_add_f32_e32 v65, v54, v65
	ds_bpermute_b32 v68, v73, v65
	v_mul_f32_e32 v55, 0xbfb8aa3b, v75
	v_exp_f32_e32 v55, v55
	v_lshlrev_b32_e32 v78, 16, v41
	v_rcp_f32_e32 v54, v0
	s_waitcnt lgkmcnt(0)
	v_add_f32_e32 v65, v65, v68
	ds_bpermute_b32 v68, v74, v65
	v_add_f32_e32 v0, 1.0, v55
	v_mul_f32_e32 v55, 0xbfb8aa3b, v78
	v_exp_f32_e32 v69, v55
	v_and_b32_e32 v79, 0xffff0000, v41
	s_waitcnt lgkmcnt(0)
	v_add_f32_e32 v65, v65, v68
	v_fmamk_f32 v65, v65, 0x3c000000, v162
	v_rcp_f32_e32 v55, v0
	v_add_f32_e32 v0, 1.0, v69
	v_mul_f32_e32 v69, 0xbfb8aa3b, v79
	v_mul_f32_e32 v68, 0x4b800000, v65
	v_cmp_gt_f32_e32 vcc, s3, v65
	v_exp_f32_e32 v69, v69
	s_nop 0
	v_cndmask_b32_e32 v65, v65, v68, vcc
	v_rsq_f32_e32 v65, v65
	v_rcp_f32_e32 v68, v0
	v_add_f32_e32 v0, 1.0, v69
	v_rcp_f32_e32 v69, v0
	v_mul_f32_e32 v0, 0x45800000, v65
	v_cndmask_b32_e32 v0, v65, v0, vcc
	v_pk_mul_f32 v[70:71], v[70:71], v[0:1] op_sel_hi:[1,0]
	v_pk_mul_f32 v[56:57], v[56:57], v[0:1] op_sel_hi:[1,0]
	v_pk_mul_f32 v[70:71], v[2:3], v[70:71]
	v_pk_mul_f32 v[56:57], v[4:5], v[56:57]
	v_pk_mul_f32 v[52:53], v[52:53], v[0:1] op_sel_hi:[1,0]
	v_pk_mul_f32 v[48:49], v[48:49], v[0:1] op_sel_hi:[1,0]
	v_pk_mul_f32 v[46:47], v[46:47], v[70:71]
	v_pk_mul_f32 v[50:51], v[50:51], v[56:57]
	v_pk_mul_f32 v[52:53], v[6:7], v[52:53]
	v_pk_mul_f32 v[48:49], v[8:9], v[48:49]
	v_pk_mul_f32 v[52:53], v[54:55], v[52:53]
	v_pk_mul_f32 v[54:55], v[68:69], v[48:49]
	v_cvt_pk_bf16_f32 v46, v46, v47
	v_cvt_pk_bf16_f32 v47, v50, v51
	v_lshlrev_b64 v[50:51], 11, v[66:67]
	v_cvt_pk_bf16_f32 v48, v52, v53
	v_cvt_pk_bf16_f32 v49, v54, v55
	v_lshl_add_u64 v[50:51], v[62:63], 0, v[50:51]
	global_store_dwordx4 v[50:51], v[46:49], off offset:512
	s_branch .LBB0_520
